# attention loops: one workgroup barrier per half-step instead of two (K restage before the barrier, V restage after it; the next half-step's barrier publishes V; loop-exit edge keeps one barrier)
# speedup vs baseline: 1.0050x; 1.0050x over previous
.Lp1join_fox_1:
	s_waitcnt vmcnt(1)
	ds_write_b128 v193, v[154:157] offset:32768
	s_waitcnt vmcnt(0)
	ds_write_b128 v193, v[158:161] offset:40960
	v_cmp_gt_f32_e32 vcc, 1.0, v108
	s_waitcnt lgkmcnt(0)
	s_barrier
	ds_write_b128 v194, v[146:149]
	ds_write_b128 v195, v[150:153]
	s_cbranch_vccz .LBB0_651
	s_and_saveexec_b64 s[0:1], s[38:39]
	ds_write_b32 v185, v108 offset:128
	s_or_b64 exec, exec, s[0:1]
	s_waitcnt lgkmcnt(0)
	ds_read_b128 v[88:91], v184 offset:224
	ds_read_b128 v[92:95], v184 offset:192
	ds_read_b128 v[110:113], v184 offset:160
	ds_read_b128 v[202:205], v184 offset:128
	s_waitcnt lgkmcnt(3)
	v_mul_f32 v64, v64, v90
	v_mul_f32 v65, v65, v91
	s_waitcnt lgkmcnt(2)
	v_mul_f32 v60, v60, v94
	v_mul_f32 v61, v61, v95
	s_waitcnt lgkmcnt(1)
	v_mul_f32 v56, v56, v112
	v_mul_f32 v57, v57, v113
	s_waitcnt lgkmcnt(0)
	v_mul_f32 v52, v52, v204
	v_mul_f32 v53, v53, v205
	v_mul_f32 v62, v62, v88
	v_mul_f32 v63, v63, v89
	v_mul_f32 v58, v58, v92
	v_mul_f32 v59, v59, v93
	v_mul_f32 v54, v54, v110
	v_mul_f32 v55, v55, v111
	v_mul_f32 v50, v50, v202
	v_mul_f32 v51, v51, v203
	v_mul_f32 v48, v48, v90
	v_mul_f32 v49, v49, v91
	v_mul_f32 v44, v44, v94
	v_mul_f32 v45, v45, v95
	v_mul_f32 v40, v40, v112
	v_mul_f32 v41, v41, v113
	v_mul_f32 v36, v36, v204
	v_mul_f32 v37, v37, v205
	v_mul_f32 v46, v46, v88
	v_mul_f32 v47, v47, v89
	v_mul_f32 v42, v42, v92
	v_mul_f32 v43, v43, v93
	v_mul_f32 v38, v38, v110
	v_mul_f32 v39, v39, v111
	v_mul_f32 v34, v34, v202
	v_mul_f32 v35, v35, v203
	v_mul_f32 v32, v32, v90
	v_mul_f32 v33, v33, v91
	v_mul_f32 v28, v28, v94
	v_mul_f32 v29, v29, v95
	v_mul_f32 v24, v24, v112
	v_mul_f32 v25, v25, v113
	v_mul_f32 v20, v20, v204
	v_mul_f32 v21, v21, v205
	v_mul_f32 v30, v30, v88
	v_mul_f32 v31, v31, v89
	v_mul_f32 v26, v26, v92
	v_mul_f32 v27, v27, v93
	v_mul_f32 v22, v22, v110
	v_mul_f32 v23, v23, v111
	v_mul_f32 v18, v18, v202
	v_mul_f32 v19, v19, v203
	v_mul_f32 v16, v16, v90
	v_mul_f32 v17, v17, v91
	v_mul_f32 v12, v12, v94
	v_mul_f32 v13, v13, v95
	v_mul_f32 v8, v8, v112
	v_mul_f32 v9, v9, v113
	v_mul_f32 v4, v4, v204
	v_mul_f32 v5, v5, v205
	v_mul_f32 v14, v14, v88
	v_mul_f32 v15, v15, v89
	v_mul_f32 v10, v10, v92
	v_mul_f32 v11, v11, v93
	v_mul_f32 v6, v6, v110
	v_mul_f32 v7, v7, v111
	v_mul_f32 v2, v2, v202
	v_mul_f32 v3, v3, v203
.LBB0_651:
	v_cndmask_b32_e64 v1, v1, v196, s[40:41]
	v_sub_f32_e32 v88, v98, v1
	v_sub_f32_e32 v89, v99, v1
	v_sub_f32_e32 v90, v100, v1
	v_sub_f32_e32 v91, v101, v1
	v_sub_f32_e32 v92, v102, v1
	v_sub_f32_e32 v93, v103, v1
	v_sub_f32_e32 v94, v104, v1
	v_sub_f32_e32 v95, v105, v1
	v_sub_f32_e32 v78, v78, v1
	v_sub_f32_e32 v79, v79, v1
	v_sub_f32_e32 v96, v106, v1
	v_sub_f32_e32 v97, v107, v1
	v_sub_f32_e32 v74, v74, v1
	v_sub_f32_e32 v75, v75, v1
	v_sub_f32_e32 v80, v80, v1
	v_sub_f32_e32 v81, v81, v1
	v_exp_f32_e32 v196, v88
	v_exp_f32_e32 v203, v89
	v_exp_f32_e32 v112, v90
	v_exp_f32_e32 v202, v91
	v_exp_f32_e32 v110, v92
	v_exp_f32_e32 v113, v93
	v_exp_f32_e32 v109, v94
	v_exp_f32_e32 v111, v95
	v_exp_f32_e32 v103, v78
	v_exp_f32_e32 v107, v79
	v_exp_f32_e32 v101, v96
	v_exp_f32_e32 v106, v97
	v_exp_f32_e32 v99, v74
	v_exp_f32_e32 v102, v75
	v_exp_f32_e32 v98, v80
	v_exp_f32_e32 v100, v81
	s_add_i32 s0, s9, 1
	s_cmp_lt_i32 s0, s25
	s_cselect_b64 s[22:23], -1, 0
	s_cmp_ge_i32 s0, s25
	s_cbranch_scc1 .LBB0_653
	v_add_u32_e32 v80, 0x41, v218
	v_mad_i64_i32 v[74:75], s[0:1], v80, s33, v[164:165]
	v_add_u32_e32 v81, 0x61, v218
	v_mad_i64_i32 v[78:79], s[0:1], v81, s33, v[164:165]
	global_load_dwordx4 v[146:149], v[74:75], off
	global_load_dwordx4 v[150:153], v[78:79], off
	v_mad_i64_i32 v[74:75], s[0:1], v80, s33, v[166:167]
	v_mad_i64_i32 v[78:79], s[0:1], v81, s33, v[166:167]
	global_load_dwordx4 v[154:157], v[74:75], off
	global_load_dwordx4 v[158:161], v[78:79], off

.Lp1join_fox_3:
	s_andn2_b64 vcc, exec, s[22:23]
	s_cbranch_vccnz .Lnok_fox
	s_waitcnt vmcnt(1)
	ds_write_b128 v193, v[154:157] offset:49152
	s_waitcnt vmcnt(0)
	ds_write_b128 v193, v[158:161] offset:57344
.Lnok_fox:
	s_waitcnt lgkmcnt(0)
	s_barrier
	s_cbranch_vccnz .LBB0_657
	ds_write_b128 v194, v[146:149] offset:16384
	ds_write_b128 v195, v[150:153] offset:16384

.LBB0_661:
	v_cndmask_b32_e64 v196, v66, v1, s[40:41]
	v_sub_f32_e32 v1, v96, v196
	v_sub_f32_e32 v66, v97, v196
	v_sub_f32_e32 v67, v84, v196
	v_sub_f32_e32 v68, v85, v196
	v_sub_f32_e32 v69, v98, v196
	v_sub_f32_e32 v72, v99, v196
	v_sub_f32_e32 v73, v88, v196
	v_sub_f32_e32 v84, v89, v196
	v_sub_f32_e32 v85, v90, v196
	v_sub_f32_e32 v88, v91, v196
	v_sub_f32_e32 v89, v92, v196
	v_sub_f32_e32 v90, v93, v196
	v_sub_f32_e32 v91, v94, v196
	v_sub_f32_e32 v92, v95, v196
	v_sub_f32_e32 v86, v86, v196
	v_sub_f32_e32 v87, v87, v196
	v_exp_f32_e32 v215, v1
	v_exp_f32_e32 v217, v66
	v_exp_f32_e32 v213, v67
	v_exp_f32_e32 v216, v68
	v_exp_f32_e32 v211, v69
	v_exp_f32_e32 v214, v72
	v_exp_f32_e32 v210, v73
	v_exp_f32_e32 v212, v84
	v_exp_f32_e32 v207, v85
	v_exp_f32_e32 v209, v88
	v_exp_f32_e32 v205, v89
	v_exp_f32_e32 v208, v90
	v_exp_f32_e32 v203, v91
	v_exp_f32_e32 v206, v92
	v_exp_f32_e32 v202, v86
	v_exp_f32_e32 v204, v87
	v_sub_f32_e32 v1, v81, v196
	v_add_f32_e32 v81, v200, v201
	v_fmac_f32_e32 v81, v197, v162
	v_add_f32_e32 v162, v104, v105
	s_addk_i32 s11, 0x80
	s_add_i32 s9, s9, 2
	v_sub_f32_e32 v67, v71, v196
	v_sub_f32_e32 v66, v70, v196
	v_sub_f32_e32 v69, v83, v196
	v_sub_f32_e32 v68, v82, v196
	v_sub_f32_e32 v71, v77, v196
	v_sub_f32_e32 v70, v76, v196
	v_sub_f32_e32 v73, v75, v196
	v_sub_f32_e32 v72, v74, v196
	v_sub_f32_e32 v75, v101, v196
	v_sub_f32_e32 v74, v100, v196
	v_sub_f32_e32 v77, v79, v196
	v_sub_f32_e32 v76, v78, v196
	v_sub_f32_e32 v79, v103, v196
	v_sub_f32_e32 v78, v102, v196
	v_fmac_f32_e32 v162, v81, v108
	v_add_u32_e32 v198, 0x200, v198
	v_add_u32_e32 v199, 0xffffff80, v199
	s_cmp_ge_i32 s9, s25
	v_sub_f32_e32 v80, v80, v196
	s_cbranch_scc1 .Lexitbar_fox
	v_mov_b32_e32 v197, v146
	s_branch .LBB0_645
.Lexitbar_fox:
	s_waitcnt lgkmcnt(0)
	s_barrier
	s_branch .LBB0_664

.Lp1join_dif_1:
	s_waitcnt vmcnt(2)
	ds_write_b128 v164, v[122:125] offset:32768
	s_waitcnt vmcnt(0)
	ds_write_b128 v164, v[126:129] offset:40960
	v_cmp_gt_f32_e32 vcc, 1.0, v181
	s_waitcnt lgkmcnt(0)
	s_barrier
	ds_write_b128 v165, v[114:117]
	ds_write_b128 v166, v[118:121]
	s_cbranch_vccz .LBB0_829
	s_and_saveexec_b64 s[0:1], s[38:39]
	ds_write_b32 v155, v181 offset:128
	s_or_b64 exec, exec, s[0:1]
	s_waitcnt lgkmcnt(0)
	ds_read_b128 v[134:137], v154 offset:224
	ds_read_b128 v[138:141], v154 offset:192
	ds_read_b128 v[142:145], v154 offset:160
	ds_read_b128 v[184:187], v154 offset:128
	s_waitcnt lgkmcnt(3)
	v_mul_f32 v64, v64, v136
	v_mul_f32 v65, v65, v137
	s_waitcnt lgkmcnt(2)
	v_mul_f32 v60, v60, v140
	v_mul_f32 v61, v61, v141
	s_waitcnt lgkmcnt(1)
	v_mul_f32 v56, v56, v144
	v_mul_f32 v57, v57, v145
	s_waitcnt lgkmcnt(0)
	v_mul_f32 v52, v52, v186
	v_mul_f32 v53, v53, v187
	v_mul_f32 v62, v62, v134
	v_mul_f32 v63, v63, v135
	v_mul_f32 v58, v58, v138
	v_mul_f32 v59, v59, v139
	v_mul_f32 v54, v54, v142
	v_mul_f32 v55, v55, v143
	v_mul_f32 v50, v50, v184
	v_mul_f32 v51, v51, v185
	v_mul_f32 v48, v48, v136
	v_mul_f32 v49, v49, v137
	v_mul_f32 v44, v44, v140
	v_mul_f32 v45, v45, v141
	v_mul_f32 v40, v40, v144
	v_mul_f32 v41, v41, v145
	v_mul_f32 v36, v36, v186
	v_mul_f32 v37, v37, v187
	v_mul_f32 v46, v46, v134
	v_mul_f32 v47, v47, v135
	v_mul_f32 v42, v42, v138
	v_mul_f32 v43, v43, v139
	v_mul_f32 v38, v38, v142
	v_mul_f32 v39, v39, v143
	v_mul_f32 v34, v34, v184
	v_mul_f32 v35, v35, v185
	v_mul_f32 v32, v32, v136
	v_mul_f32 v33, v33, v137
	v_mul_f32 v28, v28, v140
	v_mul_f32 v29, v29, v141
	v_mul_f32 v24, v24, v144
	v_mul_f32 v25, v25, v145
	v_mul_f32 v20, v20, v186
	v_mul_f32 v21, v21, v187
	v_mul_f32 v30, v30, v134
	v_mul_f32 v31, v31, v135
	v_mul_f32 v26, v26, v138
	v_mul_f32 v27, v27, v139
	v_mul_f32 v22, v22, v142
	v_mul_f32 v23, v23, v143
	v_mul_f32 v18, v18, v184
	v_mul_f32 v19, v19, v185
	v_mul_f32 v16, v16, v136
	v_mul_f32 v17, v17, v137
	v_mul_f32 v12, v12, v140
	v_mul_f32 v13, v13, v141
	v_mul_f32 v8, v8, v144
	v_mul_f32 v9, v9, v145
	v_mul_f32 v4, v4, v186
	v_mul_f32 v5, v5, v187
	v_mul_f32 v14, v14, v134
	v_mul_f32 v15, v15, v135
	v_mul_f32 v10, v10, v138
	v_mul_f32 v11, v11, v139
	v_mul_f32 v6, v6, v142
	v_mul_f32 v7, v7, v143
	v_mul_f32 v2, v2, v184
	v_mul_f32 v3, v3, v185
.LBB0_829:
	v_cndmask_b32_e64 v132, v132, v168, s[40:41]
	v_mul_f32_e32 v183, 0xbe38aa3b, v132
	v_fmamk_f32 v82, v82, 0x3e38aa3b, v183
	v_fmamk_f32 v184, v66, 0x3e38aa3b, v183
	v_fmamk_f32 v66, v83, 0x3e38aa3b, v183
	v_fmamk_f32 v185, v67, 0x3e38aa3b, v183
	v_fmamk_f32 v67, v84, 0x3e38aa3b, v183
	v_fmamk_f32 v186, v68, 0x3e38aa3b, v183
	v_fmamk_f32 v68, v85, 0x3e38aa3b, v183
	v_fmamk_f32 v187, v69, 0x3e38aa3b, v183
	v_fmamk_f32 v69, v86, 0x3e38aa3b, v183
	v_fmamk_f32 v188, v70, 0x3e38aa3b, v183
	v_fmamk_f32 v70, v87, 0x3e38aa3b, v183
	v_fmamk_f32 v189, v71, 0x3e38aa3b, v183
	v_fmamk_f32 v71, v88, 0x3e38aa3b, v183
	v_fmamk_f32 v190, v72, 0x3e38aa3b, v183
	v_fmamk_f32 v72, v89, 0x3e38aa3b, v183
	v_fmamk_f32 v191, v73, 0x3e38aa3b, v183
	v_fmamk_f32 v73, v90, 0x3e38aa3b, v183
	v_fmamk_f32 v192, v74, 0x3e38aa3b, v183
	v_fmamk_f32 v74, v91, 0x3e38aa3b, v183
	v_fmamk_f32 v193, v75, 0x3e38aa3b, v183
	v_fmamk_f32 v75, v92, 0x3e38aa3b, v183
	v_fmamk_f32 v194, v76, 0x3e38aa3b, v183
	v_fmamk_f32 v76, v93, 0x3e38aa3b, v183
	v_fmamk_f32 v195, v77, 0x3e38aa3b, v183
	v_fmamk_f32 v77, v94, 0x3e38aa3b, v183
	v_fmamk_f32 v196, v78, 0x3e38aa3b, v183
	v_fmamk_f32 v78, v95, 0x3e38aa3b, v183
	v_fmamk_f32 v83, v96, 0x3e38aa3b, v183
	v_fmamk_f32 v84, v97, 0x3e38aa3b, v183
	v_exp_f32_e32 v146, v82
	v_exp_f32_e32 v168, v66
	v_exp_f32_e32 v144, v67
	v_exp_f32_e32 v147, v68
	v_exp_f32_e32 v142, v69
	v_exp_f32_e32 v145, v70
	v_exp_f32_e32 v141, v71
	v_exp_f32_e32 v143, v72
	v_exp_f32_e32 v138, v73
	v_exp_f32_e32 v140, v74
	v_exp_f32_e32 v136, v75
	v_exp_f32_e32 v139, v76
	v_exp_f32_e32 v134, v77
	v_exp_f32_e32 v137, v78
	v_exp_f32_e32 v133, v83
	v_exp_f32_e32 v135, v84
	s_add_i32 s0, s8, 1
	s_cmp_lt_i32 s0, s27
	v_fmamk_f32 v197, v79, 0x3e38aa3b, v183
	v_fmamk_f32 v198, v80, 0x3e38aa3b, v183
	v_fmac_f32_e32 v183, 0x3e38aa3b, v81
	s_cselect_b64 s[22:23], -1, 0
	s_cmp_ge_i32 s0, s27
	s_cbranch_scc1 .LBB0_831
	v_add_u32_e32 v66, 0x41, v182
	v_mad_i64_i32 v[66:67], s[0:1], v66, s33, v[130:131]
	v_add_u32_e32 v68, 0x61, v182
	v_mad_i64_i32 v[68:69], s[0:1], v68, s33, v[130:131]
	global_load_dwordx4 v[114:117], v[66:67], off offset:2048
	global_load_dwordx4 v[122:125], v[66:67], off offset:1024
	global_load_dwordx4 v[118:121], v[68:69], off offset:2048
	global_load_dwordx4 v[126:129], v[68:69], off offset:1024

.Lp1join_dif_3:
	s_andn2_b64 vcc, exec, s[22:23]
	s_cbranch_vccnz .Lnok_dif
	s_waitcnt vmcnt(2)
	ds_write_b128 v164, v[122:125] offset:49152
	s_waitcnt vmcnt(0)
	ds_write_b128 v164, v[126:129] offset:57344
.Lnok_dif:
	s_waitcnt lgkmcnt(0)
	s_barrier
	s_cbranch_vccnz .LBB0_835
	ds_write_b128 v165, v[114:117] offset:16384
	ds_write_b128 v166, v[118:121] offset:16384

.LBB0_839:
	v_cndmask_b32_e64 v168, v115, v132, s[40:41]
	v_mul_f32_e32 v116, 0xbe38aa3b, v168
	v_mov_b32_e32 v115, v116
	v_fmamk_f32 v82, v82, 0x3e38aa3b, v116
	v_fmamk_f32 v83, v83, 0x3e38aa3b, v116
	v_fmamk_f32 v84, v84, 0x3e38aa3b, v116
	v_fmamk_f32 v85, v85, 0x3e38aa3b, v116
	v_fmamk_f32 v86, v86, 0x3e38aa3b, v116
	v_fmamk_f32 v87, v87, 0x3e38aa3b, v116
	v_fmamk_f32 v88, v88, 0x3e38aa3b, v116
	v_fmamk_f32 v89, v89, 0x3e38aa3b, v116
	v_fmamk_f32 v90, v90, 0x3e38aa3b, v116
	v_fmamk_f32 v91, v91, 0x3e38aa3b, v116
	v_fmamk_f32 v92, v92, 0x3e38aa3b, v116
	v_fmamk_f32 v93, v93, 0x3e38aa3b, v116
	v_fmamk_f32 v94, v94, 0x3e38aa3b, v116
	v_fmamk_f32 v95, v95, 0x3e38aa3b, v116
	v_fmamk_f32 v96, v96, 0x3e38aa3b, v116
	v_fmac_f32_e32 v115, 0x3e38aa3b, v97
	v_exp_f32_e32 v197, v82
	v_exp_f32_e32 v199, v83
	v_exp_f32_e32 v195, v84
	v_exp_f32_e32 v198, v85
	v_exp_f32_e32 v193, v86
	v_exp_f32_e32 v196, v87
	v_exp_f32_e32 v192, v88
	v_exp_f32_e32 v194, v89
	v_exp_f32_e32 v189, v90
	v_exp_f32_e32 v191, v91
	v_exp_f32_e32 v187, v92
	v_exp_f32_e32 v190, v93
	v_exp_f32_e32 v185, v94
	v_exp_f32_e32 v188, v95
	v_exp_f32_e32 v184, v96
	v_exp_f32_e32 v186, v115
	v_fma_f32 v146, v66, s10, v116
	v_fma_f32 v147, v67, s10, v116
	v_add_f32_e32 v66, v179, v180
	v_fmac_f32_e32 v66, v167, v157
	v_add_f32_e32 v157, v182, v183
	s_addk_i32 s9, 0x80
	s_add_i32 s8, s8, 2
	v_fma_f32 v132, v80, s10, v116
	v_fma_f32 v133, v81, s10, v116
	v_fma_f32 v134, v78, s10, v116
	v_fma_f32 v135, v79, s10, v116
	v_fma_f32 v136, v76, s10, v116
	v_fma_f32 v137, v77, s10, v116
	v_fma_f32 v138, v74, s10, v116
	v_fma_f32 v139, v75, s10, v116
	v_fma_f32 v140, v72, s10, v116
	v_fma_f32 v141, v73, s10, v116
	v_fma_f32 v142, v70, s10, v116
	v_fma_f32 v143, v71, s10, v116
	v_fma_f32 v144, v68, s10, v116
	v_fma_f32 v145, v69, s10, v116
	v_fmac_f32_e32 v157, v66, v181
	s_cmp_ge_i32 s8, s27
	v_add_u32_e32 v169, 0xffffff80, v169
	s_cbranch_scc1 .Lexitbar_dif
	v_mov_b32_e32 v167, v114
	s_branch .LBB0_823
